# L1 out-projection epilogue: gate, norm-weight and scale vectors that are identical for all 8 row groups are loaded once and kept in registers instead of reloaded per row group
# speedup vs baseline: 1.0049x; 1.0019x over previous
.LBB0_1672:
	s_lshr_b32 s14, s14, 2
	s_add_i32 s14, s14, 1
	s_and_b64 s[4:5], s[4:5], exec
	s_cselect_b32 s14, 0, s14
	s_lshl_b64 s[4:5], s[40:41], 20
	s_add_u32 s46, s68, s4
	s_addc_u32 s47, s69, s5
	s_lshl_b64 s[4:5], s[40:41], 19
	s_add_u32 s42, s59, s4
	s_addc_u32 s43, s60, s5
	v_lshl_or_b32 v174, s48, 8, v179
	s_mul_hi_u32 s20, s14, 0x6000
	s_mulk_i32 s14, 0x6000
	s_lshl_b64 s[40:41], s[40:41], 10
	v_ashrrev_i32_e32 v175, 31, v174
	s_add_u32 s4, s57, s14
	s_addc_u32 s5, s58, s20
	v_lshlrev_b64 v[214:215], 2, v[174:175]
	v_lshl_add_u64 v[176:177], s[4:5], 0, v[214:215]
	global_load_dwordx4 v[182:185], v[176:177], off
	v_lshl_add_u64 v[218:219], v[132:133], 0, v[174:175]
	v_lshlrev_b64 v[172:173], 2, v[218:219]
	v_lshl_add_u64 v[198:199], s[44:45], 0, v[172:173]
	global_load_dwordx4 v[186:189], v[198:199], off
	global_load_dwordx4 v[190:193], v[198:199], off offset:64
	global_load_dwordx4 v[194:197], v[198:199], off offset:512
	s_nop 0
	global_load_dwordx4 v[198:201], v[198:199], off offset:576
	s_add_u32 s4, s50, s14
	v_lshl_add_u64 v[220:221], s[46:47], 0, v[172:173]
	s_addc_u32 s5, s51, s20
	global_load_dwordx4 v[202:205], v[176:177], off offset:64
	global_load_dwordx4 v[206:209], v[176:177], off offset:512
	global_load_dwordx4 v[210:213], v[176:177], off offset:576
	v_lshl_add_u64 v[172:173], s[4:5], 0, v[214:215]
	v_lshl_add_u64 v[218:219], v[218:219], 1, s[42:43]
	s_waitcnt vmcnt(6)
	v_pk_fma_f32 v[184:185], v[126:127], v[184:185], v[188:189]
	v_pk_fma_f32 v[182:183], v[124:125], v[182:183], v[186:187]
	global_store_dwordx4 v[220:221], v[182:185], off
	global_load_dwordx4 v[186:189], v[172:173], off
	global_load_dwordx4 v[222:225], v[172:173], off
	v_lshl_add_u64 v[124:125], s[22:23], 0, v[214:215]
	global_load_dwordx4 v[214:217], v[124:125], off
	global_load_dwordx4 v[240:243], v[124:125], off
	s_waitcnt vmcnt(7)
	v_pk_fma_f32 v[192:193], v[122:123], v[204:205], v[192:193]
	v_pk_fma_f32 v[190:191], v[120:121], v[202:203], v[190:191]
	v_or_b32_e32 v126, 16, v174
	v_ashrrev_i32_e32 v127, 31, v126
	s_waitcnt vmcnt(6)
	v_pk_fma_f32 v[196:197], v[118:119], v[208:209], v[196:197]
	v_pk_fma_f32 v[194:195], v[116:117], v[206:207], v[194:195]
	s_waitcnt vmcnt(5)
	v_pk_fma_f32 v[200:201], v[114:115], v[212:213], v[200:201]
	v_pk_fma_f32 v[198:199], v[112:113], v[210:211], v[198:199]
	s_waitcnt vmcnt(3)
	v_pk_add_f32 v[120:121], v[188:189], 1.0 op_sel_hi:[1,0]
	v_pk_add_f32 v[122:123], v[186:187], 1.0 op_sel_hi:[1,0]
	s_waitcnt vmcnt(1)
	v_pk_mul_f32 v[120:121], v[216:217], v[120:121]
	v_pk_mul_f32 v[122:123], v[214:215], v[122:123]
	v_pk_mul_f32 v[120:121], v[184:185], v[120:121]
	v_pk_mul_f32 v[122:123], v[182:183], v[122:123]
	s_nop 0
	v_cvt_pk_bf16_f32 v122, v122, v123
	v_cvt_pk_bf16_f32 v123, v120, v121
	global_store_dwordx2 v[218:219], v[122:123], off
	global_store_dwordx4 v[220:221], v[190:193], off offset:64
	global_load_dwordx4 v[186:189], v[172:173], off offset:64
	global_load_dwordx4 v[226:229], v[172:173], off offset:64
	v_lshl_add_u64 v[120:121], v[126:127], 2, s[22:23]
	global_load_dwordx4 v[202:205], v[120:121], off
	global_load_dwordx4 v[244:247], v[120:121], off
	v_or_b32_e32 v122, 0x80, v174
	v_ashrrev_i32_e32 v123, 31, v122
	v_mul_f32_e32 v126, v195, v195
	v_mul_f32_e32 v127, v197, v197
	v_fmac_f32_e32 v126, v194, v194
	v_fmac_f32_e32 v127, v196, v196
	s_waitcnt vmcnt(3)
	v_pk_add_f32 v[116:117], v[188:189], 1.0 op_sel_hi:[1,0]
	v_pk_add_f32 v[118:119], v[186:187], 1.0 op_sel_hi:[1,0]
	s_waitcnt vmcnt(1)
	v_pk_mul_f32 v[116:117], v[204:205], v[116:117]
	v_pk_mul_f32 v[118:119], v[202:203], v[118:119]
	v_pk_mul_f32 v[116:117], v[192:193], v[116:117]
	v_pk_mul_f32 v[118:119], v[190:191], v[118:119]
	s_nop 0
	v_cvt_pk_bf16_f32 v118, v118, v119
	v_cvt_pk_bf16_f32 v119, v116, v117
	global_store_dwordx2 v[218:219], v[118:119], off offset:32
	global_store_dwordx4 v[220:221], v[194:197], off offset:512
	global_load_dwordx4 v[186:189], v[172:173], off offset:512
	global_load_dwordx4 v[232:235], v[172:173], off offset:512
	v_lshl_add_u64 v[116:117], v[122:123], 2, s[22:23]
	global_load_dwordx4 v[202:205], v[116:117], off
	global_load_dwordx4 v[248:251], v[116:117], off
	v_or_b32_e32 v118, 0x90, v174
	v_ashrrev_i32_e32 v119, 31, v118
	v_mul_f32_e32 v122, v191, v191
	v_mul_f32_e32 v123, v193, v193
	v_fmac_f32_e32 v122, v190, v190
	v_fmac_f32_e32 v123, v192, v192
	s_waitcnt vmcnt(3)
	v_pk_add_f32 v[112:113], v[188:189], 1.0 op_sel_hi:[1,0]
	v_pk_add_f32 v[114:115], v[186:187], 1.0 op_sel_hi:[1,0]
	s_waitcnt vmcnt(1)
	v_pk_mul_f32 v[112:113], v[204:205], v[112:113]
	v_pk_mul_f32 v[114:115], v[202:203], v[114:115]
	v_pk_mul_f32 v[112:113], v[196:197], v[112:113]
	v_pk_mul_f32 v[114:115], v[194:195], v[114:115]
	s_nop 0
	v_cvt_pk_bf16_f32 v114, v114, v115
	v_cvt_pk_bf16_f32 v115, v112, v113
	global_store_dwordx2 v[218:219], v[114:115], off offset:256
	global_store_dwordx4 v[220:221], v[198:201], off offset:576
	global_load_dwordx4 v[186:189], v[172:173], off offset:576
	global_load_dwordx4 v[236:239], v[172:173], off offset:576
	v_lshl_add_u64 v[112:113], v[118:119], 2, s[22:23]
	global_load_dwordx4 v[202:205], v[112:113], off
	v_mul_f32_e32 v118, v183, v183
	v_mul_f32_e32 v119, v185, v185
	v_and_b32_e32 v115, 64, v181
	v_fmac_f32_e32 v118, v182, v182
	v_fmac_f32_e32 v119, v184, v184
	v_xor_b32_e32 v114, 16, v181
	v_add_u32_e32 v115, 64, v115
	v_mul_f32_e32 v183, v199, v199
	v_mul_f32_e32 v185, v201, v201
	v_add_f32_e32 v118, v118, v119
	v_add_f32_e32 v119, v122, v123
	v_cmp_lt_i32_e32 vcc, v114, v115
	v_fmac_f32_e32 v183, v198, v198
	v_fmac_f32_e32 v185, v200, v200
	v_add_f32_e32 v122, v126, v127
	v_add_f32_e32 v118, v118, v119
	v_cndmask_b32_e32 v114, v181, v114, vcc
	v_add_f32_e32 v123, v183, v185
	v_add_f32_e32 v118, v118, v122
	v_lshlrev_b32_e32 v114, 2, v114
	v_add_f32_e32 v118, v118, v123
	ds_bpermute_b32 v119, v114, v118
	v_xor_b32_e32 v122, 32, v181
	v_cmp_lt_i32_e32 vcc, v122, v115
	s_waitcnt lgkmcnt(0)
	v_add_f32_e32 v118, v118, v119
	v_cndmask_b32_e32 v115, v181, v122, vcc
	v_lshlrev_b32_e32 v115, 2, v115
	ds_bpermute_b32 v119, v115, v118
	s_waitcnt vmcnt(2)
	v_pk_add_f32 v[122:123], v[188:189], 1.0 op_sel_hi:[1,0]
	v_pk_add_f32 v[126:127], v[186:187], 1.0 op_sel_hi:[1,0]
	s_waitcnt vmcnt(0)
	v_pk_mul_f32 v[122:123], v[204:205], v[122:123]
	v_pk_mul_f32 v[126:127], v[202:203], v[126:127]
	v_pk_mul_f32 v[122:123], v[200:201], v[122:123]
	v_pk_mul_f32 v[126:127], v[198:199], v[126:127]
	s_nop 0
	v_cvt_pk_bf16_f32 v126, v126, v127
	v_cvt_pk_bf16_f32 v127, v122, v123
	global_store_dwordx2 v[218:219], v[126:127], off offset:288
	s_and_saveexec_b64 s[4:5], s[6:7]
	s_cbranch_execz .LBB0_1674
	s_waitcnt lgkmcnt(0)
	v_add_f32_e32 v122, v118, v119
	v_lshl_add_u64 v[118:119], v[148:149], 0, s[40:41]
	global_atomic_add_f32 v[118:119], v122, off
.LBB0_1674:
	s_or_b64 exec, exec, s[4:5]
	s_waitcnt lgkmcnt(0)
	v_lshl_add_u64 v[118:119], v[134:135], 0, v[174:175]
	v_lshlrev_b64 v[122:123], 2, v[118:119]
	v_lshl_add_u64 v[126:127], s[44:45], 0, v[122:123]
	global_load_dwordx4 v[182:185], v[126:127], off
	global_load_dwordx4 v[186:189], v[176:177], off
	global_load_dwordx4 v[190:193], v[176:177], off offset:64
	global_load_dwordx4 v[194:197], v[176:177], off offset:512
	global_load_dwordx4 v[198:201], v[176:177], off offset:576
	v_lshl_add_u64 v[122:123], s[46:47], 0, v[122:123]
	global_load_dwordx4 v[202:205], v[126:127], off offset:64
	global_load_dwordx4 v[206:209], v[126:127], off offset:512
	global_load_dwordx4 v[210:213], v[126:127], off offset:576
	v_lshl_add_u64 v[118:119], v[118:119], 1, s[42:43]
	s_waitcnt vmcnt(6)
	v_pk_fma_f32 v[110:111], v[110:111], v[188:189], v[184:185]
	v_pk_fma_f32 v[108:109], v[108:109], v[186:187], v[182:183]
	global_store_dwordx4 v[122:123], v[108:111], off
	v_mov_b32_e32 v182, v222
	v_mov_b32_e32 v183, v223
	v_mov_b32_e32 v184, v224
	v_mov_b32_e32 v185, v225
	v_mov_b32_e32 v186, v240
	v_mov_b32_e32 v187, v241
	v_mov_b32_e32 v188, v242
	v_mov_b32_e32 v189, v243
	s_waitcnt vmcnt(3)
	v_pk_fma_f32 v[106:107], v[106:107], v[192:193], v[204:205]
	v_pk_fma_f32 v[104:105], v[104:105], v[190:191], v[202:203]
	s_waitcnt vmcnt(2)
	v_pk_fma_f32 v[102:103], v[102:103], v[196:197], v[208:209]
	v_pk_fma_f32 v[100:101], v[100:101], v[194:195], v[206:207]
	s_waitcnt vmcnt(1)
	v_pk_fma_f32 v[192:193], v[98:99], v[200:201], v[212:213]
	v_pk_fma_f32 v[190:191], v[96:97], v[198:199], v[210:211]
	v_pk_add_f32 v[126:127], v[184:185], 1.0 op_sel_hi:[1,0]
	v_pk_add_f32 v[182:183], v[182:183], 1.0 op_sel_hi:[1,0]
	v_pk_mul_f32 v[126:127], v[188:189], v[126:127]
	v_pk_mul_f32 v[182:183], v[186:187], v[182:183]
	v_pk_mul_f32 v[126:127], v[110:111], v[126:127]
	v_pk_mul_f32 v[182:183], v[108:109], v[182:183]
	s_nop 0
	v_cvt_pk_bf16_f32 v182, v182, v183
	v_cvt_pk_bf16_f32 v183, v126, v127
	global_store_dwordx2 v[118:119], v[182:183], off
	global_store_dwordx4 v[122:123], v[104:107], off offset:64
	v_mov_b32_e32 v182, v226
	v_mov_b32_e32 v183, v227
	v_mov_b32_e32 v184, v228
	v_mov_b32_e32 v185, v229
	s_nop 0
	v_mov_b32_e32 v186, v244
	v_mov_b32_e32 v187, v245
	v_mov_b32_e32 v188, v246
	v_mov_b32_e32 v189, v247
	v_pk_add_f32 v[126:127], v[184:185], 1.0 op_sel_hi:[1,0]
	v_pk_add_f32 v[182:183], v[182:183], 1.0 op_sel_hi:[1,0]
	v_pk_mul_f32 v[126:127], v[188:189], v[126:127]
	v_pk_mul_f32 v[182:183], v[186:187], v[182:183]
	v_pk_mul_f32 v[126:127], v[106:107], v[126:127]
	v_pk_mul_f32 v[182:183], v[104:105], v[182:183]
	s_nop 0
	v_cvt_pk_bf16_f32 v182, v182, v183
	v_cvt_pk_bf16_f32 v183, v126, v127
	global_store_dwordx2 v[118:119], v[182:183], off offset:32
	global_store_dwordx4 v[122:123], v[100:103], off offset:512
	v_mov_b32_e32 v182, v232
	v_mov_b32_e32 v183, v233
	v_mov_b32_e32 v184, v234
	v_mov_b32_e32 v185, v235
	s_nop 0
	v_mov_b32_e32 v186, v248
	v_mov_b32_e32 v187, v249
	v_mov_b32_e32 v188, v250
	v_mov_b32_e32 v189, v251
	v_pk_add_f32 v[96:97], v[184:185], 1.0 op_sel_hi:[1,0]
	v_pk_add_f32 v[98:99], v[182:183], 1.0 op_sel_hi:[1,0]
	v_pk_mul_f32 v[96:97], v[188:189], v[96:97]
	v_pk_mul_f32 v[98:99], v[186:187], v[98:99]
	v_pk_mul_f32 v[96:97], v[102:103], v[96:97]
	v_pk_mul_f32 v[98:99], v[100:101], v[98:99]
	v_mul_f32_e32 v101, v101, v101
	v_cvt_pk_bf16_f32 v98, v98, v99
	v_cvt_pk_bf16_f32 v99, v96, v97
	global_store_dwordx2 v[118:119], v[98:99], off offset:256
	global_store_dwordx4 v[122:123], v[190:193], off offset:576
	v_mov_b32_e32 v182, v236
	v_mov_b32_e32 v183, v237
	v_mov_b32_e32 v184, v238
	v_mov_b32_e32 v185, v239
	global_load_dwordx4 v[186:189], v[112:113], off
	v_mul_f32_e32 v96, v109, v109
	v_mul_f32_e32 v97, v111, v111
	v_mul_f32_e32 v98, v105, v105
	v_mul_f32_e32 v99, v107, v107
	v_mul_f32_e32 v103, v103, v103
	v_fmac_f32_e32 v96, v108, v108
	v_fmac_f32_e32 v97, v110, v110
	v_fmac_f32_e32 v98, v104, v104
	v_fmac_f32_e32 v99, v106, v106
	v_mul_f32_e32 v105, v191, v191
	v_mul_f32_e32 v107, v193, v193
	v_fmac_f32_e32 v101, v100, v100
	v_fmac_f32_e32 v103, v102, v102
	v_add_f32_e32 v96, v96, v97
	v_add_f32_e32 v97, v98, v99
	v_fmac_f32_e32 v105, v190, v190
	v_fmac_f32_e32 v107, v192, v192
	v_add_f32_e32 v98, v101, v103
	v_add_f32_e32 v96, v96, v97
	v_add_f32_e32 v99, v105, v107
	v_add_f32_e32 v96, v96, v98
	v_add_f32_e32 v96, v96, v99
	ds_bpermute_b32 v97, v114, v96
	s_waitcnt lgkmcnt(0)
	v_add_f32_e32 v96, v96, v97
	ds_bpermute_b32 v97, v115, v96
	v_pk_add_f32 v[98:99], v[184:185], 1.0 op_sel_hi:[1,0]
	v_pk_add_f32 v[100:101], v[182:183], 1.0 op_sel_hi:[1,0]
	s_waitcnt vmcnt(0)
	v_pk_mul_f32 v[98:99], v[188:189], v[98:99]
	v_pk_mul_f32 v[100:101], v[186:187], v[100:101]
	v_pk_mul_f32 v[98:99], v[192:193], v[98:99]
	v_pk_mul_f32 v[100:101], v[190:191], v[100:101]
	s_nop 0
	v_cvt_pk_bf16_f32 v100, v100, v101
	v_cvt_pk_bf16_f32 v101, v98, v99
	global_store_dwordx2 v[118:119], v[100:101], off offset:288
	s_and_saveexec_b64 s[4:5], s[6:7]
	s_cbranch_execz .LBB0_1676
	s_waitcnt lgkmcnt(0)
	v_add_f32_e32 v98, v96, v97
	v_lshl_add_u64 v[96:97], v[150:151], 0, s[40:41]
	global_atomic_add_f32 v[96:97], v98, off
.LBB0_1676:
	s_or_b64 exec, exec, s[4:5]
	v_lshl_add_u64 v[118:119], v[136:137], 0, v[174:175]
	v_lshlrev_b64 v[122:123], 2, v[118:119]
	v_lshl_add_u64 v[126:127], s[44:45], 0, v[122:123]
	s_waitcnt lgkmcnt(0)
	global_load_dwordx4 v[96:99], v[126:127], off
	global_load_dwordx4 v[100:103], v[176:177], off
	global_load_dwordx4 v[104:107], v[176:177], off offset:64
	global_load_dwordx4 v[108:111], v[176:177], off offset:512
	global_load_dwordx4 v[182:185], v[176:177], off offset:576
	v_lshl_add_u64 v[122:123], s[46:47], 0, v[122:123]
	global_load_dwordx4 v[186:189], v[126:127], off offset:64
	global_load_dwordx4 v[190:193], v[126:127], off offset:512
	global_load_dwordx4 v[194:197], v[126:127], off offset:576
	v_lshl_add_u64 v[118:119], v[118:119], 1, s[42:43]
	s_waitcnt vmcnt(6)
	v_pk_fma_f32 v[94:95], v[94:95], v[102:103], v[98:99]
	v_pk_fma_f32 v[92:93], v[92:93], v[100:101], v[96:97]
	global_store_dwordx4 v[122:123], v[92:95], off
	v_mov_b32_e32 v96, v222
	v_mov_b32_e32 v97, v223
	v_mov_b32_e32 v98, v224
	v_mov_b32_e32 v99, v225
	v_mov_b32_e32 v100, v240
	v_mov_b32_e32 v101, v241
	v_mov_b32_e32 v102, v242
	v_mov_b32_e32 v103, v243
	s_waitcnt vmcnt(3)
	v_pk_fma_f32 v[90:91], v[90:91], v[106:107], v[188:189]
	v_pk_fma_f32 v[88:89], v[88:89], v[104:105], v[186:187]
	s_waitcnt vmcnt(2)
	v_pk_fma_f32 v[86:87], v[86:87], v[110:111], v[192:193]
	v_pk_fma_f32 v[84:85], v[84:85], v[108:109], v[190:191]
	s_waitcnt vmcnt(1)
	v_pk_fma_f32 v[106:107], v[82:83], v[184:185], v[196:197]
	v_pk_fma_f32 v[104:105], v[80:81], v[182:183], v[194:195]
	v_pk_add_f32 v[98:99], v[98:99], 1.0 op_sel_hi:[1,0]
	v_pk_add_f32 v[96:97], v[96:97], 1.0 op_sel_hi:[1,0]
	v_pk_mul_f32 v[98:99], v[102:103], v[98:99]
	v_pk_mul_f32 v[96:97], v[100:101], v[96:97]
	v_pk_mul_f32 v[98:99], v[94:95], v[98:99]
	v_pk_mul_f32 v[96:97], v[92:93], v[96:97]
	s_nop 0
	v_cvt_pk_bf16_f32 v96, v96, v97
	v_cvt_pk_bf16_f32 v97, v98, v99
	global_store_dwordx2 v[118:119], v[96:97], off
	global_store_dwordx4 v[122:123], v[88:91], off offset:64
	v_mov_b32_e32 v96, v226
	v_mov_b32_e32 v97, v227
	v_mov_b32_e32 v98, v228
	v_mov_b32_e32 v99, v229
	s_nop 0
	v_mov_b32_e32 v100, v244
	v_mov_b32_e32 v101, v245
	v_mov_b32_e32 v102, v246
	v_mov_b32_e32 v103, v247
	v_pk_add_f32 v[98:99], v[98:99], 1.0 op_sel_hi:[1,0]
	v_pk_add_f32 v[96:97], v[96:97], 1.0 op_sel_hi:[1,0]
	v_pk_mul_f32 v[98:99], v[102:103], v[98:99]
	v_pk_mul_f32 v[96:97], v[100:101], v[96:97]
	v_pk_mul_f32 v[98:99], v[90:91], v[98:99]
	v_pk_mul_f32 v[96:97], v[88:89], v[96:97]
	s_nop 0
	v_cvt_pk_bf16_f32 v96, v96, v97
	v_cvt_pk_bf16_f32 v97, v98, v99
	global_store_dwordx2 v[118:119], v[96:97], off offset:32
	global_store_dwordx4 v[122:123], v[84:87], off offset:512
	v_mov_b32_e32 v96, v232
	v_mov_b32_e32 v97, v233
	v_mov_b32_e32 v98, v234
	v_mov_b32_e32 v99, v235
	s_nop 0
	v_mov_b32_e32 v100, v248
	v_mov_b32_e32 v101, v249
	v_mov_b32_e32 v102, v250
	v_mov_b32_e32 v103, v251
	v_pk_add_f32 v[80:81], v[98:99], 1.0 op_sel_hi:[1,0]
	v_pk_add_f32 v[82:83], v[96:97], 1.0 op_sel_hi:[1,0]
	v_pk_mul_f32 v[80:81], v[102:103], v[80:81]
	v_pk_mul_f32 v[82:83], v[100:101], v[82:83]
	v_pk_mul_f32 v[80:81], v[86:87], v[80:81]
	v_pk_mul_f32 v[82:83], v[84:85], v[82:83]
	v_mul_f32_e32 v85, v85, v85
	v_cvt_pk_bf16_f32 v82, v82, v83
	v_cvt_pk_bf16_f32 v83, v80, v81
	global_store_dwordx2 v[118:119], v[82:83], off offset:256
	global_store_dwordx4 v[122:123], v[104:107], off offset:576
	v_mov_b32_e32 v96, v236
	v_mov_b32_e32 v97, v237
	v_mov_b32_e32 v98, v238
	v_mov_b32_e32 v99, v239
	global_load_dwordx4 v[100:103], v[112:113], off
	v_mul_f32_e32 v80, v93, v93
	v_mul_f32_e32 v81, v95, v95
	v_mul_f32_e32 v82, v89, v89
	v_mul_f32_e32 v83, v91, v91
	v_mul_f32_e32 v87, v87, v87
	v_fmac_f32_e32 v80, v92, v92
	v_fmac_f32_e32 v81, v94, v94
	v_fmac_f32_e32 v82, v88, v88
	v_fmac_f32_e32 v83, v90, v90
	v_mul_f32_e32 v89, v105, v105
	v_mul_f32_e32 v91, v107, v107
	v_fmac_f32_e32 v85, v84, v84
	v_fmac_f32_e32 v87, v86, v86
	v_add_f32_e32 v80, v80, v81
	v_add_f32_e32 v81, v82, v83
	v_fmac_f32_e32 v89, v104, v104
	v_fmac_f32_e32 v91, v106, v106
	v_add_f32_e32 v82, v85, v87
	v_add_f32_e32 v80, v80, v81
	v_add_f32_e32 v83, v89, v91
	v_add_f32_e32 v80, v80, v82
	v_add_f32_e32 v80, v80, v83
	ds_bpermute_b32 v81, v114, v80
	s_waitcnt lgkmcnt(0)
	v_add_f32_e32 v80, v80, v81
	ds_bpermute_b32 v81, v115, v80
	v_pk_add_f32 v[82:83], v[98:99], 1.0 op_sel_hi:[1,0]
	v_pk_add_f32 v[84:85], v[96:97], 1.0 op_sel_hi:[1,0]
	s_waitcnt vmcnt(0)
	v_pk_mul_f32 v[82:83], v[102:103], v[82:83]
	v_pk_mul_f32 v[84:85], v[100:101], v[84:85]
	v_pk_mul_f32 v[82:83], v[106:107], v[82:83]
	v_pk_mul_f32 v[84:85], v[104:105], v[84:85]
	s_nop 0
	v_cvt_pk_bf16_f32 v84, v84, v85
	v_cvt_pk_bf16_f32 v85, v82, v83
	global_store_dwordx2 v[118:119], v[84:85], off offset:288
	s_and_saveexec_b64 s[4:5], s[6:7]
	s_cbranch_execz .LBB0_1678
	s_waitcnt lgkmcnt(0)
	v_add_f32_e32 v82, v80, v81
	v_lshl_add_u64 v[80:81], v[152:153], 0, s[40:41]
	global_atomic_add_f32 v[80:81], v82, off
.LBB0_1678:
	s_or_b64 exec, exec, s[4:5]
	v_lshl_add_u64 v[118:119], v[138:139], 0, v[174:175]
	v_lshlrev_b64 v[100:101], 2, v[118:119]
	v_lshl_add_u64 v[108:109], s[44:45], 0, v[100:101]
	s_waitcnt lgkmcnt(0)
	global_load_dwordx4 v[80:83], v[108:109], off
	global_load_dwordx4 v[84:87], v[176:177], off
	global_load_dwordx4 v[88:91], v[176:177], off offset:64
	global_load_dwordx4 v[92:95], v[176:177], off offset:512
	global_load_dwordx4 v[96:99], v[176:177], off offset:576
	v_lshl_add_u64 v[122:123], s[46:47], 0, v[100:101]
	global_load_dwordx4 v[100:103], v[108:109], off offset:64
	global_load_dwordx4 v[104:107], v[108:109], off offset:512
	s_nop 0
	global_load_dwordx4 v[108:111], v[108:109], off offset:576
	v_lshl_add_u64 v[118:119], v[118:119], 1, s[42:43]
	s_waitcnt vmcnt(6)
	v_pk_fma_f32 v[78:79], v[78:79], v[86:87], v[82:83]
	v_pk_fma_f32 v[76:77], v[76:77], v[84:85], v[80:81]
	global_store_dwordx4 v[122:123], v[76:79], off
	v_mov_b32_e32 v80, v222
	v_mov_b32_e32 v81, v223
	v_mov_b32_e32 v82, v224
	v_mov_b32_e32 v83, v225
	v_mov_b32_e32 v84, v240
	v_mov_b32_e32 v85, v241
	v_mov_b32_e32 v86, v242
	v_mov_b32_e32 v87, v243
	s_waitcnt vmcnt(3)
	v_pk_fma_f32 v[74:75], v[74:75], v[90:91], v[102:103]
	v_pk_fma_f32 v[72:73], v[72:73], v[88:89], v[100:101]
	s_waitcnt vmcnt(2)
	v_pk_fma_f32 v[70:71], v[70:71], v[94:95], v[106:107]
	v_pk_fma_f32 v[68:69], v[68:69], v[92:93], v[104:105]
	s_waitcnt vmcnt(1)
	v_pk_fma_f32 v[90:91], v[66:67], v[98:99], v[110:111]
	v_pk_fma_f32 v[88:89], v[64:65], v[96:97], v[108:109]
	v_pk_add_f32 v[82:83], v[82:83], 1.0 op_sel_hi:[1,0]
	v_pk_add_f32 v[80:81], v[80:81], 1.0 op_sel_hi:[1,0]
	v_pk_mul_f32 v[82:83], v[86:87], v[82:83]
	v_pk_mul_f32 v[80:81], v[84:85], v[80:81]
	v_pk_mul_f32 v[82:83], v[78:79], v[82:83]
	v_pk_mul_f32 v[80:81], v[76:77], v[80:81]
	s_nop 0
	v_cvt_pk_bf16_f32 v80, v80, v81
	v_cvt_pk_bf16_f32 v81, v82, v83
	global_store_dwordx2 v[118:119], v[80:81], off
	global_store_dwordx4 v[122:123], v[72:75], off offset:64
	v_mov_b32_e32 v80, v226
	v_mov_b32_e32 v81, v227
	v_mov_b32_e32 v82, v228
	v_mov_b32_e32 v83, v229
	s_nop 0
	v_mov_b32_e32 v84, v244
	v_mov_b32_e32 v85, v245
	v_mov_b32_e32 v86, v246
	v_mov_b32_e32 v87, v247
	v_pk_add_f32 v[82:83], v[82:83], 1.0 op_sel_hi:[1,0]
	v_pk_add_f32 v[80:81], v[80:81], 1.0 op_sel_hi:[1,0]
	v_pk_mul_f32 v[82:83], v[86:87], v[82:83]
	v_pk_mul_f32 v[80:81], v[84:85], v[80:81]
	v_pk_mul_f32 v[82:83], v[74:75], v[82:83]
	v_pk_mul_f32 v[80:81], v[72:73], v[80:81]
	s_nop 0
	v_cvt_pk_bf16_f32 v80, v80, v81
	v_cvt_pk_bf16_f32 v81, v82, v83
	global_store_dwordx2 v[118:119], v[80:81], off offset:32
	global_store_dwordx4 v[122:123], v[68:71], off offset:512
	v_mov_b32_e32 v80, v232
	v_mov_b32_e32 v81, v233
	v_mov_b32_e32 v82, v234
	v_mov_b32_e32 v83, v235
	s_nop 0
	v_mov_b32_e32 v84, v248
	v_mov_b32_e32 v85, v249
	v_mov_b32_e32 v86, v250
	v_mov_b32_e32 v87, v251
	v_pk_add_f32 v[64:65], v[82:83], 1.0 op_sel_hi:[1,0]
	v_pk_add_f32 v[66:67], v[80:81], 1.0 op_sel_hi:[1,0]
	v_pk_mul_f32 v[64:65], v[86:87], v[64:65]
	v_pk_mul_f32 v[66:67], v[84:85], v[66:67]
	v_pk_mul_f32 v[64:65], v[70:71], v[64:65]
	v_pk_mul_f32 v[66:67], v[68:69], v[66:67]
	v_mul_f32_e32 v69, v69, v69
	v_cvt_pk_bf16_f32 v66, v66, v67
	v_cvt_pk_bf16_f32 v67, v64, v65
	global_store_dwordx2 v[118:119], v[66:67], off offset:256
	global_store_dwordx4 v[122:123], v[88:91], off offset:576
	v_mov_b32_e32 v80, v236
	v_mov_b32_e32 v81, v237
	v_mov_b32_e32 v82, v238
	v_mov_b32_e32 v83, v239
	global_load_dwordx4 v[84:87], v[112:113], off
	v_mul_f32_e32 v64, v77, v77
	v_mul_f32_e32 v65, v79, v79
	v_mul_f32_e32 v66, v73, v73
	v_mul_f32_e32 v67, v75, v75
	v_mul_f32_e32 v71, v71, v71
	v_fmac_f32_e32 v64, v76, v76
	v_fmac_f32_e32 v65, v78, v78
	v_fmac_f32_e32 v66, v72, v72
	v_fmac_f32_e32 v67, v74, v74
	v_mul_f32_e32 v73, v89, v89
	v_mul_f32_e32 v75, v91, v91
	v_fmac_f32_e32 v69, v68, v68
	v_fmac_f32_e32 v71, v70, v70
	v_add_f32_e32 v64, v64, v65
	v_add_f32_e32 v65, v66, v67
	v_fmac_f32_e32 v73, v88, v88
	v_fmac_f32_e32 v75, v90, v90
	v_add_f32_e32 v66, v69, v71
	v_add_f32_e32 v64, v64, v65
	v_add_f32_e32 v67, v73, v75
	v_add_f32_e32 v64, v64, v66
	v_add_f32_e32 v64, v64, v67
	ds_bpermute_b32 v65, v114, v64
	s_waitcnt lgkmcnt(0)
	v_add_f32_e32 v64, v64, v65
	ds_bpermute_b32 v65, v115, v64
	v_pk_add_f32 v[66:67], v[82:83], 1.0 op_sel_hi:[1,0]
	v_pk_add_f32 v[68:69], v[80:81], 1.0 op_sel_hi:[1,0]
	s_waitcnt vmcnt(0)
	v_pk_mul_f32 v[66:67], v[86:87], v[66:67]
	v_pk_mul_f32 v[68:69], v[84:85], v[68:69]
	v_pk_mul_f32 v[66:67], v[90:91], v[66:67]
	v_pk_mul_f32 v[68:69], v[88:89], v[68:69]
	s_nop 0
	v_cvt_pk_bf16_f32 v68, v68, v69
	v_cvt_pk_bf16_f32 v69, v66, v67
	global_store_dwordx2 v[118:119], v[68:69], off offset:288
	s_and_saveexec_b64 s[4:5], s[6:7]
	s_cbranch_execz .LBB0_1680
	s_waitcnt lgkmcnt(0)
	v_add_f32_e32 v66, v64, v65
	v_lshl_add_u64 v[64:65], v[154:155], 0, s[40:41]
	global_atomic_add_f32 v[64:65], v66, off
.LBB0_1680:
	s_or_b64 exec, exec, s[4:5]
	v_lshl_add_u64 v[96:97], v[140:141], 0, v[174:175]
	v_lshlrev_b64 v[84:85], 2, v[96:97]
	v_lshl_add_u64 v[92:93], s[44:45], 0, v[84:85]
	s_waitcnt lgkmcnt(0)
	global_load_dwordx4 v[64:67], v[92:93], off
	global_load_dwordx4 v[68:71], v[176:177], off
	global_load_dwordx4 v[72:75], v[176:177], off offset:64
	global_load_dwordx4 v[76:79], v[176:177], off offset:512
	global_load_dwordx4 v[80:83], v[176:177], off offset:576
	v_lshl_add_u64 v[98:99], s[46:47], 0, v[84:85]
	global_load_dwordx4 v[84:87], v[92:93], off offset:64
	global_load_dwordx4 v[88:91], v[92:93], off offset:512
	s_nop 0
	global_load_dwordx4 v[92:95], v[92:93], off offset:576
	v_lshl_add_u64 v[96:97], v[96:97], 1, s[42:43]
	s_waitcnt vmcnt(6)
	v_pk_fma_f32 v[62:63], v[62:63], v[70:71], v[66:67]
	v_pk_fma_f32 v[60:61], v[60:61], v[68:69], v[64:65]
	global_store_dwordx4 v[98:99], v[60:63], off
	v_mov_b32_e32 v64, v222
	v_mov_b32_e32 v65, v223
	v_mov_b32_e32 v66, v224
	v_mov_b32_e32 v67, v225
	v_mov_b32_e32 v68, v240
	v_mov_b32_e32 v69, v241
	v_mov_b32_e32 v70, v242
	v_mov_b32_e32 v71, v243
	s_waitcnt vmcnt(3)
	v_pk_fma_f32 v[58:59], v[58:59], v[74:75], v[86:87]
	v_pk_fma_f32 v[56:57], v[56:57], v[72:73], v[84:85]
	s_waitcnt vmcnt(2)
	v_pk_fma_f32 v[54:55], v[54:55], v[78:79], v[90:91]
	v_pk_fma_f32 v[52:53], v[52:53], v[76:77], v[88:89]
	s_waitcnt vmcnt(1)
	v_pk_fma_f32 v[74:75], v[50:51], v[82:83], v[94:95]
	v_pk_fma_f32 v[72:73], v[48:49], v[80:81], v[92:93]
	v_pk_add_f32 v[66:67], v[66:67], 1.0 op_sel_hi:[1,0]
	v_pk_add_f32 v[64:65], v[64:65], 1.0 op_sel_hi:[1,0]
	v_pk_mul_f32 v[66:67], v[70:71], v[66:67]
	v_pk_mul_f32 v[64:65], v[68:69], v[64:65]
	v_pk_mul_f32 v[66:67], v[62:63], v[66:67]
	v_pk_mul_f32 v[64:65], v[60:61], v[64:65]
	s_nop 0
	v_cvt_pk_bf16_f32 v64, v64, v65
	v_cvt_pk_bf16_f32 v65, v66, v67
	global_store_dwordx2 v[96:97], v[64:65], off
	global_store_dwordx4 v[98:99], v[56:59], off offset:64
	v_mov_b32_e32 v64, v226
	v_mov_b32_e32 v65, v227
	v_mov_b32_e32 v66, v228
	v_mov_b32_e32 v67, v229
	s_nop 0
	v_mov_b32_e32 v68, v244
	v_mov_b32_e32 v69, v245
	v_mov_b32_e32 v70, v246
	v_mov_b32_e32 v71, v247
	v_pk_add_f32 v[66:67], v[66:67], 1.0 op_sel_hi:[1,0]
	v_pk_add_f32 v[64:65], v[64:65], 1.0 op_sel_hi:[1,0]
	v_pk_mul_f32 v[66:67], v[70:71], v[66:67]
	v_pk_mul_f32 v[64:65], v[68:69], v[64:65]
	v_pk_mul_f32 v[66:67], v[58:59], v[66:67]
	v_pk_mul_f32 v[64:65], v[56:57], v[64:65]
	s_nop 0
	v_cvt_pk_bf16_f32 v64, v64, v65
	v_cvt_pk_bf16_f32 v65, v66, v67
	global_store_dwordx2 v[96:97], v[64:65], off offset:32
	global_store_dwordx4 v[98:99], v[52:55], off offset:512
	v_mov_b32_e32 v64, v232
	v_mov_b32_e32 v65, v233
	v_mov_b32_e32 v66, v234
	v_mov_b32_e32 v67, v235
	s_nop 0
	v_mov_b32_e32 v68, v248
	v_mov_b32_e32 v69, v249
	v_mov_b32_e32 v70, v250
	v_mov_b32_e32 v71, v251
	v_pk_add_f32 v[48:49], v[66:67], 1.0 op_sel_hi:[1,0]
	v_pk_add_f32 v[50:51], v[64:65], 1.0 op_sel_hi:[1,0]
	v_pk_mul_f32 v[48:49], v[70:71], v[48:49]
	v_pk_mul_f32 v[50:51], v[68:69], v[50:51]
	v_pk_mul_f32 v[48:49], v[54:55], v[48:49]
	v_pk_mul_f32 v[50:51], v[52:53], v[50:51]
	v_mul_f32_e32 v53, v53, v53
	v_cvt_pk_bf16_f32 v50, v50, v51
	v_cvt_pk_bf16_f32 v51, v48, v49
	global_store_dwordx2 v[96:97], v[50:51], off offset:256
	global_store_dwordx4 v[98:99], v[72:75], off offset:576
	v_mov_b32_e32 v64, v236
	v_mov_b32_e32 v65, v237
	v_mov_b32_e32 v66, v238
	v_mov_b32_e32 v67, v239
	global_load_dwordx4 v[68:71], v[112:113], off
	v_mul_f32_e32 v48, v61, v61
	v_mul_f32_e32 v49, v63, v63
	v_mul_f32_e32 v50, v57, v57
	v_mul_f32_e32 v51, v59, v59
	v_mul_f32_e32 v55, v55, v55
	v_fmac_f32_e32 v48, v60, v60
	v_fmac_f32_e32 v49, v62, v62
	v_fmac_f32_e32 v50, v56, v56
	v_fmac_f32_e32 v51, v58, v58
	v_mul_f32_e32 v57, v73, v73
	v_mul_f32_e32 v59, v75, v75
	v_fmac_f32_e32 v53, v52, v52
	v_fmac_f32_e32 v55, v54, v54
	v_add_f32_e32 v48, v48, v49
	v_add_f32_e32 v49, v50, v51
	v_fmac_f32_e32 v57, v72, v72
	v_fmac_f32_e32 v59, v74, v74
	v_add_f32_e32 v50, v53, v55
	v_add_f32_e32 v48, v48, v49
	v_add_f32_e32 v51, v57, v59
	v_add_f32_e32 v48, v48, v50
	v_add_f32_e32 v48, v48, v51
	ds_bpermute_b32 v49, v114, v48
	s_waitcnt lgkmcnt(0)
	v_add_f32_e32 v48, v48, v49
	ds_bpermute_b32 v49, v115, v48
	v_pk_add_f32 v[50:51], v[66:67], 1.0 op_sel_hi:[1,0]
	v_pk_add_f32 v[52:53], v[64:65], 1.0 op_sel_hi:[1,0]
	s_waitcnt vmcnt(0)
	v_pk_mul_f32 v[50:51], v[70:71], v[50:51]
	v_pk_mul_f32 v[52:53], v[68:69], v[52:53]
	v_pk_mul_f32 v[50:51], v[74:75], v[50:51]
	v_pk_mul_f32 v[52:53], v[72:73], v[52:53]
	s_nop 0
	v_cvt_pk_bf16_f32 v52, v52, v53
	v_cvt_pk_bf16_f32 v53, v50, v51
	global_store_dwordx2 v[96:97], v[52:53], off offset:288
	s_and_saveexec_b64 s[4:5], s[6:7]
	s_cbranch_execz .LBB0_1682
	s_waitcnt lgkmcnt(0)
	v_add_f32_e32 v50, v48, v49
	v_lshl_add_u64 v[48:49], v[156:157], 0, s[40:41]
	global_atomic_add_f32 v[48:49], v50, off
.LBB0_1682:
	s_or_b64 exec, exec, s[4:5]
	v_lshl_add_u64 v[80:81], v[142:143], 0, v[174:175]
	v_lshlrev_b64 v[68:69], 2, v[80:81]
	v_lshl_add_u64 v[76:77], s[44:45], 0, v[68:69]
	s_waitcnt lgkmcnt(0)
	global_load_dwordx4 v[48:51], v[76:77], off
	global_load_dwordx4 v[52:55], v[176:177], off
	global_load_dwordx4 v[56:59], v[176:177], off offset:64
	global_load_dwordx4 v[60:63], v[176:177], off offset:512
	global_load_dwordx4 v[64:67], v[176:177], off offset:576
	v_lshl_add_u64 v[82:83], s[46:47], 0, v[68:69]
	global_load_dwordx4 v[68:71], v[76:77], off offset:64
	global_load_dwordx4 v[72:75], v[76:77], off offset:512
	s_nop 0
	global_load_dwordx4 v[76:79], v[76:77], off offset:576
	v_lshl_add_u64 v[80:81], v[80:81], 1, s[42:43]
	s_waitcnt vmcnt(6)
	v_pk_fma_f32 v[46:47], v[46:47], v[54:55], v[50:51]
	v_pk_fma_f32 v[44:45], v[44:45], v[52:53], v[48:49]
	global_store_dwordx4 v[82:83], v[44:47], off
	v_mov_b32_e32 v48, v222
	v_mov_b32_e32 v49, v223
	v_mov_b32_e32 v50, v224
	v_mov_b32_e32 v51, v225
	v_mov_b32_e32 v52, v240
	v_mov_b32_e32 v53, v241
	v_mov_b32_e32 v54, v242
	v_mov_b32_e32 v55, v243
	s_waitcnt vmcnt(3)
	v_pk_fma_f32 v[42:43], v[42:43], v[58:59], v[70:71]
	v_pk_fma_f32 v[40:41], v[40:41], v[56:57], v[68:69]
	s_waitcnt vmcnt(2)
	v_pk_fma_f32 v[38:39], v[38:39], v[62:63], v[74:75]
	v_pk_fma_f32 v[36:37], v[36:37], v[60:61], v[72:73]
	s_waitcnt vmcnt(1)
	v_pk_fma_f32 v[58:59], v[34:35], v[66:67], v[78:79]
	v_pk_fma_f32 v[56:57], v[32:33], v[64:65], v[76:77]
	v_pk_add_f32 v[50:51], v[50:51], 1.0 op_sel_hi:[1,0]
	v_pk_add_f32 v[48:49], v[48:49], 1.0 op_sel_hi:[1,0]
	v_pk_mul_f32 v[50:51], v[54:55], v[50:51]
	v_pk_mul_f32 v[48:49], v[52:53], v[48:49]
	v_pk_mul_f32 v[50:51], v[46:47], v[50:51]
	v_pk_mul_f32 v[48:49], v[44:45], v[48:49]
	s_nop 0
	v_cvt_pk_bf16_f32 v48, v48, v49
	v_cvt_pk_bf16_f32 v49, v50, v51
	global_store_dwordx2 v[80:81], v[48:49], off
	global_store_dwordx4 v[82:83], v[40:43], off offset:64
	v_mov_b32_e32 v48, v226
	v_mov_b32_e32 v49, v227
	v_mov_b32_e32 v50, v228
	v_mov_b32_e32 v51, v229
	s_nop 0
	v_mov_b32_e32 v52, v244
	v_mov_b32_e32 v53, v245
	v_mov_b32_e32 v54, v246
	v_mov_b32_e32 v55, v247
	v_pk_add_f32 v[50:51], v[50:51], 1.0 op_sel_hi:[1,0]
	v_pk_add_f32 v[48:49], v[48:49], 1.0 op_sel_hi:[1,0]
	v_pk_mul_f32 v[50:51], v[54:55], v[50:51]
	v_pk_mul_f32 v[48:49], v[52:53], v[48:49]
	v_pk_mul_f32 v[50:51], v[42:43], v[50:51]
	v_pk_mul_f32 v[48:49], v[40:41], v[48:49]
	s_nop 0
	v_cvt_pk_bf16_f32 v48, v48, v49
	v_cvt_pk_bf16_f32 v49, v50, v51
	global_store_dwordx2 v[80:81], v[48:49], off offset:32
	global_store_dwordx4 v[82:83], v[36:39], off offset:512
	v_mov_b32_e32 v48, v232
	v_mov_b32_e32 v49, v233
	v_mov_b32_e32 v50, v234
	v_mov_b32_e32 v51, v235
	s_nop 0
	v_mov_b32_e32 v52, v248
	v_mov_b32_e32 v53, v249
	v_mov_b32_e32 v54, v250
	v_mov_b32_e32 v55, v251
	v_pk_add_f32 v[32:33], v[50:51], 1.0 op_sel_hi:[1,0]
	v_pk_add_f32 v[34:35], v[48:49], 1.0 op_sel_hi:[1,0]
	v_pk_mul_f32 v[32:33], v[54:55], v[32:33]
	v_pk_mul_f32 v[34:35], v[52:53], v[34:35]
	v_pk_mul_f32 v[32:33], v[38:39], v[32:33]
	v_pk_mul_f32 v[34:35], v[36:37], v[34:35]
	v_mul_f32_e32 v37, v37, v37
	v_cvt_pk_bf16_f32 v34, v34, v35
	v_cvt_pk_bf16_f32 v35, v32, v33
	global_store_dwordx2 v[80:81], v[34:35], off offset:256
	global_store_dwordx4 v[82:83], v[56:59], off offset:576
	v_mov_b32_e32 v48, v236
	v_mov_b32_e32 v49, v237
	v_mov_b32_e32 v50, v238
	v_mov_b32_e32 v51, v239
	global_load_dwordx4 v[52:55], v[112:113], off
	v_mul_f32_e32 v32, v45, v45
	v_mul_f32_e32 v33, v47, v47
	v_mul_f32_e32 v34, v41, v41
	v_mul_f32_e32 v35, v43, v43
	v_mul_f32_e32 v39, v39, v39
	v_fmac_f32_e32 v32, v44, v44
	v_fmac_f32_e32 v33, v46, v46
	v_fmac_f32_e32 v34, v40, v40
	v_fmac_f32_e32 v35, v42, v42
	v_mul_f32_e32 v41, v57, v57
	v_mul_f32_e32 v43, v59, v59
	v_fmac_f32_e32 v37, v36, v36
	v_fmac_f32_e32 v39, v38, v38
	v_add_f32_e32 v32, v32, v33
	v_add_f32_e32 v33, v34, v35
	v_fmac_f32_e32 v41, v56, v56
	v_fmac_f32_e32 v43, v58, v58
	v_add_f32_e32 v34, v37, v39
	v_add_f32_e32 v32, v32, v33
	v_add_f32_e32 v35, v41, v43
	v_add_f32_e32 v32, v32, v34
	v_add_f32_e32 v32, v32, v35
	ds_bpermute_b32 v33, v114, v32
	s_waitcnt lgkmcnt(0)
	v_add_f32_e32 v32, v32, v33
	ds_bpermute_b32 v33, v115, v32
	v_pk_add_f32 v[34:35], v[50:51], 1.0 op_sel_hi:[1,0]
	v_pk_add_f32 v[36:37], v[48:49], 1.0 op_sel_hi:[1,0]
	s_waitcnt vmcnt(0)
	v_pk_mul_f32 v[34:35], v[54:55], v[34:35]
	v_pk_mul_f32 v[36:37], v[52:53], v[36:37]
	v_pk_mul_f32 v[34:35], v[58:59], v[34:35]
	v_pk_mul_f32 v[36:37], v[56:57], v[36:37]
	s_nop 0
	v_cvt_pk_bf16_f32 v36, v36, v37
	v_cvt_pk_bf16_f32 v37, v34, v35
	global_store_dwordx2 v[80:81], v[36:37], off offset:288
	s_and_saveexec_b64 s[4:5], s[6:7]
	s_cbranch_execz .LBB0_1684
	s_waitcnt lgkmcnt(0)
	v_add_f32_e32 v34, v32, v33
	v_lshl_add_u64 v[32:33], v[158:159], 0, s[40:41]
	global_atomic_add_f32 v[32:33], v34, off
.LBB0_1684:
	s_or_b64 exec, exec, s[4:5]
	v_lshl_add_u64 v[64:65], v[144:145], 0, v[174:175]
	v_lshlrev_b64 v[52:53], 2, v[64:65]
	v_lshl_add_u64 v[60:61], s[44:45], 0, v[52:53]
	s_waitcnt lgkmcnt(0)
	global_load_dwordx4 v[32:35], v[60:61], off
	global_load_dwordx4 v[36:39], v[176:177], off
	global_load_dwordx4 v[40:43], v[176:177], off offset:64
	global_load_dwordx4 v[44:47], v[176:177], off offset:512
	global_load_dwordx4 v[48:51], v[176:177], off offset:576
	v_lshl_add_u64 v[66:67], s[46:47], 0, v[52:53]
	global_load_dwordx4 v[52:55], v[60:61], off offset:64
	global_load_dwordx4 v[56:59], v[60:61], off offset:512
	s_nop 0
	global_load_dwordx4 v[60:63], v[60:61], off offset:576
	v_lshl_add_u64 v[64:65], v[64:65], 1, s[42:43]
	s_waitcnt vmcnt(6)
	v_pk_fma_f32 v[30:31], v[30:31], v[38:39], v[34:35]
	v_pk_fma_f32 v[28:29], v[28:29], v[36:37], v[32:33]
	global_store_dwordx4 v[66:67], v[28:31], off
	v_mov_b32_e32 v32, v222
	v_mov_b32_e32 v33, v223
	v_mov_b32_e32 v34, v224
	v_mov_b32_e32 v35, v225
	v_mov_b32_e32 v36, v240
	v_mov_b32_e32 v37, v241
	v_mov_b32_e32 v38, v242
	v_mov_b32_e32 v39, v243
	s_waitcnt vmcnt(3)
	v_pk_fma_f32 v[26:27], v[26:27], v[42:43], v[54:55]
	v_pk_fma_f32 v[24:25], v[24:25], v[40:41], v[52:53]
	s_waitcnt vmcnt(2)
	v_pk_fma_f32 v[22:23], v[22:23], v[46:47], v[58:59]
	v_pk_fma_f32 v[20:21], v[20:21], v[44:45], v[56:57]
	s_waitcnt vmcnt(1)
	v_pk_fma_f32 v[42:43], v[18:19], v[50:51], v[62:63]
	v_pk_fma_f32 v[40:41], v[16:17], v[48:49], v[60:61]
	v_pk_add_f32 v[34:35], v[34:35], 1.0 op_sel_hi:[1,0]
	v_pk_add_f32 v[32:33], v[32:33], 1.0 op_sel_hi:[1,0]
	v_pk_mul_f32 v[34:35], v[38:39], v[34:35]
	v_pk_mul_f32 v[32:33], v[36:37], v[32:33]
	v_pk_mul_f32 v[34:35], v[30:31], v[34:35]
	v_pk_mul_f32 v[32:33], v[28:29], v[32:33]
	s_nop 0
	v_cvt_pk_bf16_f32 v32, v32, v33
	v_cvt_pk_bf16_f32 v33, v34, v35
	global_store_dwordx2 v[64:65], v[32:33], off
	global_store_dwordx4 v[66:67], v[24:27], off offset:64
	v_mov_b32_e32 v32, v226
	v_mov_b32_e32 v33, v227
	v_mov_b32_e32 v34, v228
	v_mov_b32_e32 v35, v229
	s_nop 0
	v_mov_b32_e32 v36, v244
	v_mov_b32_e32 v37, v245
	v_mov_b32_e32 v38, v246
	v_mov_b32_e32 v39, v247
	v_pk_add_f32 v[34:35], v[34:35], 1.0 op_sel_hi:[1,0]
	v_pk_add_f32 v[32:33], v[32:33], 1.0 op_sel_hi:[1,0]
	v_pk_mul_f32 v[34:35], v[38:39], v[34:35]
	v_pk_mul_f32 v[32:33], v[36:37], v[32:33]
	v_pk_mul_f32 v[34:35], v[26:27], v[34:35]
	v_pk_mul_f32 v[32:33], v[24:25], v[32:33]
	s_nop 0
	v_cvt_pk_bf16_f32 v32, v32, v33
	v_cvt_pk_bf16_f32 v33, v34, v35
	global_store_dwordx2 v[64:65], v[32:33], off offset:32
	global_store_dwordx4 v[66:67], v[20:23], off offset:512
	v_mov_b32_e32 v32, v232
	v_mov_b32_e32 v33, v233
	v_mov_b32_e32 v34, v234
	v_mov_b32_e32 v35, v235
	s_nop 0
	v_mov_b32_e32 v36, v248
	v_mov_b32_e32 v37, v249
	v_mov_b32_e32 v38, v250
	v_mov_b32_e32 v39, v251
	v_pk_add_f32 v[16:17], v[34:35], 1.0 op_sel_hi:[1,0]
	v_pk_add_f32 v[18:19], v[32:33], 1.0 op_sel_hi:[1,0]
	v_pk_mul_f32 v[16:17], v[38:39], v[16:17]
	v_pk_mul_f32 v[18:19], v[36:37], v[18:19]
	v_pk_mul_f32 v[16:17], v[22:23], v[16:17]
	v_pk_mul_f32 v[18:19], v[20:21], v[18:19]
	v_mul_f32_e32 v21, v21, v21
	v_cvt_pk_bf16_f32 v18, v18, v19
	v_cvt_pk_bf16_f32 v19, v16, v17
	global_store_dwordx2 v[64:65], v[18:19], off offset:256
	global_store_dwordx4 v[66:67], v[40:43], off offset:576
	v_mov_b32_e32 v32, v236
	v_mov_b32_e32 v33, v237
	v_mov_b32_e32 v34, v238
	v_mov_b32_e32 v35, v239
	global_load_dwordx4 v[36:39], v[112:113], off
	v_mul_f32_e32 v16, v29, v29
	v_mul_f32_e32 v17, v31, v31
	v_mul_f32_e32 v18, v25, v25
	v_mul_f32_e32 v19, v27, v27
	v_mul_f32_e32 v23, v23, v23
	v_fmac_f32_e32 v16, v28, v28
	v_fmac_f32_e32 v17, v30, v30
	v_fmac_f32_e32 v18, v24, v24
	v_fmac_f32_e32 v19, v26, v26
	v_mul_f32_e32 v25, v41, v41
	v_mul_f32_e32 v27, v43, v43
	v_fmac_f32_e32 v21, v20, v20
	v_fmac_f32_e32 v23, v22, v22
	v_add_f32_e32 v16, v16, v17
	v_add_f32_e32 v17, v18, v19
	v_fmac_f32_e32 v25, v40, v40
	v_fmac_f32_e32 v27, v42, v42
	v_add_f32_e32 v18, v21, v23
	v_add_f32_e32 v16, v16, v17
	v_add_f32_e32 v19, v25, v27
	v_add_f32_e32 v16, v16, v18
	v_add_f32_e32 v16, v16, v19
	ds_bpermute_b32 v17, v114, v16
	s_waitcnt lgkmcnt(0)
	v_add_f32_e32 v16, v16, v17
	ds_bpermute_b32 v17, v115, v16
	v_pk_add_f32 v[18:19], v[34:35], 1.0 op_sel_hi:[1,0]
	v_pk_add_f32 v[20:21], v[32:33], 1.0 op_sel_hi:[1,0]
	s_waitcnt vmcnt(0)
	v_pk_mul_f32 v[18:19], v[38:39], v[18:19]
	v_pk_mul_f32 v[20:21], v[36:37], v[20:21]
	v_pk_mul_f32 v[18:19], v[42:43], v[18:19]
	v_pk_mul_f32 v[20:21], v[40:41], v[20:21]
	s_nop 0
	v_cvt_pk_bf16_f32 v20, v20, v21
	v_cvt_pk_bf16_f32 v21, v18, v19
	global_store_dwordx2 v[64:65], v[20:21], off offset:288
	s_and_saveexec_b64 s[4:5], s[6:7]
	s_cbranch_execz .LBB0_1686
	s_waitcnt lgkmcnt(0)
	v_add_f32_e32 v18, v16, v17
	v_lshl_add_u64 v[16:17], v[160:161], 0, s[40:41]
	global_atomic_add_f32 v[16:17], v18, off
.LBB0_1686:
	s_or_b64 exec, exec, s[4:5]
	v_lshl_add_u64 v[48:49], v[146:147], 0, v[174:175]
	v_lshlrev_b64 v[36:37], 2, v[48:49]
	v_lshl_add_u64 v[44:45], s[44:45], 0, v[36:37]
	s_waitcnt lgkmcnt(0)
	global_load_dwordx4 v[16:19], v[44:45], off
	global_load_dwordx4 v[20:23], v[176:177], off
	global_load_dwordx4 v[24:27], v[176:177], off offset:64
	global_load_dwordx4 v[28:31], v[176:177], off offset:512
	global_load_dwordx4 v[32:35], v[176:177], off offset:576
	v_lshl_add_u64 v[50:51], s[46:47], 0, v[36:37]
	global_load_dwordx4 v[36:39], v[44:45], off offset:64
	global_load_dwordx4 v[40:43], v[44:45], off offset:512
	s_nop 0
	global_load_dwordx4 v[44:47], v[44:45], off offset:576
	v_lshl_add_u64 v[48:49], v[48:49], 1, s[42:43]
	s_waitcnt vmcnt(6)
	v_pk_fma_f32 v[14:15], v[14:15], v[22:23], v[18:19]
	v_pk_fma_f32 v[12:13], v[12:13], v[20:21], v[16:17]
	global_store_dwordx4 v[50:51], v[12:15], off
	v_mov_b32_e32 v16, v222
	v_mov_b32_e32 v17, v223
	v_mov_b32_e32 v18, v224
	v_mov_b32_e32 v19, v225
	v_mov_b32_e32 v20, v240
	v_mov_b32_e32 v21, v241
	v_mov_b32_e32 v22, v242
	v_mov_b32_e32 v23, v243
	s_waitcnt vmcnt(3)
	v_pk_fma_f32 v[10:11], v[10:11], v[26:27], v[38:39]
	v_pk_fma_f32 v[8:9], v[8:9], v[24:25], v[36:37]
	s_waitcnt vmcnt(2)
	v_pk_fma_f32 v[6:7], v[6:7], v[30:31], v[42:43]
	v_pk_fma_f32 v[4:5], v[4:5], v[28:29], v[40:41]
	s_waitcnt vmcnt(1)
	v_pk_fma_f32 v[26:27], v[2:3], v[34:35], v[46:47]
	v_pk_fma_f32 v[24:25], v[0:1], v[32:33], v[44:45]
	v_pk_add_f32 v[18:19], v[18:19], 1.0 op_sel_hi:[1,0]
	v_pk_add_f32 v[16:17], v[16:17], 1.0 op_sel_hi:[1,0]
	v_pk_mul_f32 v[18:19], v[22:23], v[18:19]
	v_pk_mul_f32 v[16:17], v[20:21], v[16:17]
	v_pk_mul_f32 v[18:19], v[14:15], v[18:19]
	v_pk_mul_f32 v[16:17], v[12:13], v[16:17]
	s_nop 0
	v_cvt_pk_bf16_f32 v16, v16, v17
	v_cvt_pk_bf16_f32 v17, v18, v19
	global_store_dwordx2 v[48:49], v[16:17], off
	global_store_dwordx4 v[50:51], v[8:11], off offset:64
	v_mov_b32_e32 v16, v226
	v_mov_b32_e32 v17, v227
	v_mov_b32_e32 v18, v228
	v_mov_b32_e32 v19, v229
	s_nop 0
	v_mov_b32_e32 v20, v244
	v_mov_b32_e32 v21, v245
	v_mov_b32_e32 v22, v246
	v_mov_b32_e32 v23, v247
	v_pk_add_f32 v[18:19], v[18:19], 1.0 op_sel_hi:[1,0]
	v_pk_add_f32 v[16:17], v[16:17], 1.0 op_sel_hi:[1,0]
	v_pk_mul_f32 v[18:19], v[22:23], v[18:19]
	v_pk_mul_f32 v[16:17], v[20:21], v[16:17]
	v_pk_mul_f32 v[18:19], v[10:11], v[18:19]
	v_pk_mul_f32 v[16:17], v[8:9], v[16:17]
	s_nop 0
	v_cvt_pk_bf16_f32 v16, v16, v17
	v_cvt_pk_bf16_f32 v17, v18, v19
	global_store_dwordx2 v[48:49], v[16:17], off offset:32
	global_store_dwordx4 v[50:51], v[4:7], off offset:512
	v_mov_b32_e32 v16, v232
	v_mov_b32_e32 v17, v233
	v_mov_b32_e32 v18, v234
	v_mov_b32_e32 v19, v235
	s_nop 0
	v_mov_b32_e32 v20, v248
	v_mov_b32_e32 v21, v249
	v_mov_b32_e32 v22, v250
	v_mov_b32_e32 v23, v251
	v_pk_add_f32 v[0:1], v[18:19], 1.0 op_sel_hi:[1,0]
	v_pk_add_f32 v[2:3], v[16:17], 1.0 op_sel_hi:[1,0]
	v_pk_mul_f32 v[0:1], v[22:23], v[0:1]
	v_pk_mul_f32 v[2:3], v[20:21], v[2:3]
	v_pk_mul_f32 v[0:1], v[6:7], v[0:1]
	v_pk_mul_f32 v[2:3], v[4:5], v[2:3]
	v_mul_f32_e32 v5, v5, v5
	v_cvt_pk_bf16_f32 v2, v2, v3
	v_cvt_pk_bf16_f32 v3, v0, v1
	global_store_dwordx2 v[48:49], v[2:3], off offset:256
	global_store_dwordx4 v[50:51], v[24:27], off offset:576
	v_mov_b32_e32 v16, v236
	v_mov_b32_e32 v17, v237
	v_mov_b32_e32 v18, v238
	v_mov_b32_e32 v19, v239
	global_load_dwordx4 v[20:23], v[112:113], off
	v_mul_f32_e32 v0, v13, v13
	v_mul_f32_e32 v1, v15, v15
	v_mul_f32_e32 v2, v9, v9
	v_mul_f32_e32 v3, v11, v11
	v_mul_f32_e32 v7, v7, v7
	v_fmac_f32_e32 v0, v12, v12
	v_fmac_f32_e32 v1, v14, v14
	v_fmac_f32_e32 v2, v8, v8
	v_fmac_f32_e32 v3, v10, v10
	v_mul_f32_e32 v9, v25, v25
	v_mul_f32_e32 v11, v27, v27
	v_fmac_f32_e32 v5, v4, v4
	v_fmac_f32_e32 v7, v6, v6
	v_add_f32_e32 v0, v0, v1
	v_add_f32_e32 v1, v2, v3
	v_fmac_f32_e32 v9, v24, v24
	v_fmac_f32_e32 v11, v26, v26
	v_add_f32_e32 v2, v5, v7
	v_add_f32_e32 v0, v0, v1
	v_add_f32_e32 v3, v9, v11
	v_add_f32_e32 v0, v0, v2
	v_add_f32_e32 v0, v0, v3
	ds_bpermute_b32 v1, v114, v0
	s_waitcnt lgkmcnt(0)
	v_add_f32_e32 v0, v0, v1
	ds_bpermute_b32 v1, v115, v0
	v_pk_add_f32 v[2:3], v[18:19], 1.0 op_sel_hi:[1,0]
	v_pk_add_f32 v[4:5], v[16:17], 1.0 op_sel_hi:[1,0]
	s_waitcnt vmcnt(0)
	v_pk_mul_f32 v[2:3], v[22:23], v[2:3]
	v_pk_mul_f32 v[4:5], v[20:21], v[4:5]
	v_pk_mul_f32 v[2:3], v[26:27], v[2:3]
	v_pk_mul_f32 v[4:5], v[24:25], v[4:5]
	s_nop 0
	v_cvt_pk_bf16_f32 v4, v4, v5
	v_cvt_pk_bf16_f32 v5, v2, v3
	global_store_dwordx2 v[48:49], v[4:5], off offset:288
	s_and_saveexec_b64 s[4:5], s[6:7]
	s_cbranch_execz .LBB0_1688
	s_waitcnt lgkmcnt(0)
	v_add_f32_e32 v2, v0, v1
	v_lshl_add_u64 v[0:1], v[162:163], 0, s[40:41]
	global_atomic_add_f32 v[0:1], v2, off
